# attention tile body: cross-half row-max exchange by v_permlane32_swap instead of ds_bpermute + lgkmcnt(0) (no LDS round trip; V^T reads stay in flight until the PV MFMAs)
# baseline (speedup 1.0000x reference)
; __device__ __forceinline__ void attn_block_unit(LAS unsigned char* lds, const bf16* QB, bf16* OB, const bf16* KB, const bf16* VB, int sb, int hp, int cp, const float* tab, int tid) {
;     ...
;             float tm = fmaxf(s0[0], s1[0]);
; #pragma unroll
;             for (int r = 1; r < 16; ++r) tm = fmaxf(tm, fmaxf(s0[r], s1[r]));
;             tm = fmaxf(tm, __shfl_xor(tm, 32));
;             const float mn = fmaxf(mrun, tm), sc = __expf(mrun - mn); mrun = mn;
;             float ps = 0.f;
; #pragma unroll
;             for (int r = 0; r < 16; ++r) { s0[r] = __expf(s0[r] - mn); s1[r] = __expf(s1[r] - mn); ps += s0[r] + s1[r]; }
;             lrun = lrun * sc + ps;
; #pragma unroll
;             for (int r = 0; r < 16; ++r) { oT[0][r] *= sc; oT[1][r] *= sc; }
.Latt_softmax:
	v_max3_f32 v36, v84, v85, v86
	v_max3_f32 v37, v87, v88, v89
	v_max3_f32 v38, v90, v91, v92
	v_max3_f32 v39, v93, v94, v95
	v_max3_f32 v40, v96, v97, v98
	v_max3_f32 v41, v99, v68, v69
	v_max3_f32 v42, v70, v71, v72
	v_max3_f32 v43, v73, v74, v75
	v_max3_f32 v44, v76, v77, v78
	v_max3_f32 v45, v79, v80, v81
	v_max3_f32 v46, v82, v83, v36
	v_max3_f32 v37, v37, v38, v39
	v_max3_f32 v40, v40, v41, v42
	v_max3_f32 v43, v43, v44, v45
	v_max3_f32 v37, v37, v40, v43
	v_max_f32_e32 v64, v37, v46
	v_mov_b32_e32 v65, v64
	s_nop 1
	v_permlane32_swap_b32_e32 v65, v64
	v_max_f32_e32 v64, v64, v65
	v_add_f32_e32 v64, v64, v66
	v_sub_f32_e32 v63, v64, v215
	v_cmp_lt_f32_e32 vcc, 0x40b17218, v63
	s_cbranch_vccz .Latt_keep_max
	v_max_f32_e32 v67, v215, v64
	v_sub_f32_e32 v63, v215, v67
	v_mul_f32_e32 v63, 0x3fb8aa3b, v63
	v_exp_f32_e32 v52, v63
	v_mov_b32_e32 v215, v67
	v_pk_mul_f32 v[34:35], v[34:35], v[52:53] op_sel_hi:[1,0]
	v_pk_mul_f32 v[32:33], v[32:33], v[52:53] op_sel_hi:[1,0]
	v_pk_mul_f32 v[30:31], v[30:31], v[52:53] op_sel_hi:[1,0]
	v_pk_mul_f32 v[28:29], v[28:29], v[52:53] op_sel_hi:[1,0]
	v_pk_mul_f32 v[26:27], v[26:27], v[52:53] op_sel_hi:[1,0]
	v_pk_mul_f32 v[24:25], v[24:25], v[52:53] op_sel_hi:[1,0]
	v_pk_mul_f32 v[22:23], v[22:23], v[52:53] op_sel_hi:[1,0]
	v_pk_mul_f32 v[20:21], v[20:21], v[52:53] op_sel_hi:[1,0]
	v_pk_mul_f32 v[18:19], v[18:19], v[52:53] op_sel_hi:[1,0]
	v_pk_mul_f32 v[16:17], v[16:17], v[52:53] op_sel_hi:[1,0]
	v_pk_mul_f32 v[14:15], v[14:15], v[52:53] op_sel_hi:[1,0]
	v_pk_mul_f32 v[12:13], v[12:13], v[52:53] op_sel_hi:[1,0]
	v_pk_mul_f32 v[10:11], v[10:11], v[52:53] op_sel_hi:[1,0]
	v_pk_mul_f32 v[8:9], v[8:9], v[52:53] op_sel_hi:[1,0]
	v_pk_mul_f32 v[6:7], v[6:7], v[52:53] op_sel_hi:[1,0]
	v_pk_mul_f32 v[4:5], v[4:5], v[52:53] op_sel_hi:[1,0]
	v_mul_f32_e32 v214, v214, v52
